# v19 plus the same 32-bit/u24 integer arithmetic at the remaining sites of the sample attention loop (prologue loads, the two late loop loads, the rr*f multiplies)
# baseline (speedup 1.0000x reference)
.LBB0_1283:
	v_lshlrev_b32_e32 v120, 11, v140
	v_lshl_add_u64 v[2:3], s[60:61], 0, v[120:121]
	v_mov_b32_e32 v143, v121
	v_lshl_add_u64 v[2:3], v[142:143], 1, v[2:3]
	v_lshlrev_b32_e32 v120, 1, v122
	v_lshl_add_u64 v[2:3], v[2:3], 0, v[120:121]
	v_add_u32_e32 v1, v179, v155
	global_load_dwordx4 v[56:59], v[2:3], off
	global_load_dwordx4 v[60:63], v[2:3], off offset:32
	global_load_dwordx4 v[52:55], v[2:3], off offset:64
	global_load_dwordx4 v[48:51], v[2:3], off offset:96
	v_min_i32_e32 v2, s53, v1
	v_mul_u32_u24_e32 v2, v2, v177
	v_add_u32_e32 v2, v2, v178
	v_add_u32_e32 v3, -8, v2
	v_cmp_lt_i32_e32 vcc, v2, v180
	v_cmp_ne_u32_e64 s[10:11], 0, v0
	v_cmp_eq_u32_e64 s[80:81], 1, v0
	v_cndmask_b32_e32 v2, v3, v2, vcc
	v_mul_u32_u24_e32 v2, v2, v141
	v_mov_b32_e32 v3, 0
	v_or_b32_e32 v2, v2, v130
	v_cndmask_b32_e32 v5, v145, v149, vcc
	v_cndmask_b32_e32 v4, v144, v148, vcc
	v_lshlrev_b32_e32 v2, 2, v2
	v_lshl_add_u64 v[4:5], v[4:5], 0, v[2:3]
	global_load_dwordx4 v[112:115], v[4:5], off
	v_cndmask_b32_e32 v5, v147, v151, vcc
	v_cndmask_b32_e32 v4, v146, v150, vcc
	v_lshl_add_u64 v[2:3], v[4:5], 0, v[2:3]
	global_load_dwordx4 v[116:119], v[2:3], off
	v_add_u32_e32 v2, 4, v1
	v_min_i32_e32 v2, s53, v2
	v_mul_u32_u24_e32 v2, v2, v177
	v_add_u32_e32 v2, v2, v178
	v_add_u32_e32 v3, -8, v2
	v_cmp_lt_i32_e32 vcc, v2, v180
	v_mul_u32_u24_e32 v199, v177, v1
	s_lshl_b32 s51, s18, 5
	v_cndmask_b32_e32 v2, v3, v2, vcc
	v_mul_u32_u24_e32 v2, v2, v141
	v_mov_b32_e32 v3, 0
	v_or_b32_e32 v2, v2, v130
	v_cndmask_b32_e32 v5, v145, v149, vcc
	v_cndmask_b32_e32 v4, v144, v148, vcc
	v_lshlrev_b32_e32 v2, 2, v2
	v_lshl_add_u64 v[4:5], v[4:5], 0, v[2:3]
	global_load_dwordx4 v[104:107], v[4:5], off
	v_cndmask_b32_e32 v5, v147, v151, vcc
	v_cndmask_b32_e32 v4, v146, v150, vcc
	v_lshl_add_u64 v[2:3], v[4:5], 0, v[2:3]
	global_load_dwordx4 v[108:111], v[2:3], off
	v_add_u32_e32 v2, 8, v1
	v_min_i32_e32 v2, s53, v2
	v_mul_u32_u24_e32 v2, v2, v177
	v_add_u32_e32 v2, v2, v178
	v_add_u32_e32 v3, -8, v2
	v_cmp_lt_i32_e32 vcc, v2, v180
	v_lshlrev_b32_e32 v185, 5, v177
	v_mov_b32_e32 v202, 0
	v_cndmask_b32_e32 v2, v3, v2, vcc
	v_mul_u32_u24_e32 v2, v2, v141
	v_mov_b32_e32 v3, 0
	v_or_b32_e32 v2, v2, v130
	v_cndmask_b32_e32 v5, v145, v149, vcc
	v_cndmask_b32_e32 v4, v144, v148, vcc
	v_lshlrev_b32_e32 v2, 2, v2
	v_lshl_add_u64 v[4:5], v[4:5], 0, v[2:3]
	global_load_dwordx4 v[96:99], v[4:5], off
	v_cndmask_b32_e32 v5, v147, v151, vcc
	v_cndmask_b32_e32 v4, v146, v150, vcc
	v_lshl_add_u64 v[2:3], v[4:5], 0, v[2:3]
	global_load_dwordx4 v[100:103], v[2:3], off
	v_add_u32_e32 v2, 12, v1
	v_min_i32_e32 v2, s53, v2
	v_mul_u32_u24_e32 v2, v2, v177
	v_add_u32_e32 v2, v2, v178
	v_add_u32_e32 v3, -8, v2
	v_cmp_lt_i32_e32 vcc, v2, v180
	s_mov_b32 s33, 0
	s_add_i32 s48, s53, -4
	v_cndmask_b32_e32 v2, v3, v2, vcc
	v_mul_u32_u24_e32 v2, v2, v141
	v_mov_b32_e32 v3, 0
	v_or_b32_e32 v2, v2, v130
	v_cndmask_b32_e32 v5, v145, v149, vcc
	v_cndmask_b32_e32 v4, v144, v148, vcc
	v_lshlrev_b32_e32 v2, 2, v2
	v_lshl_add_u64 v[4:5], v[4:5], 0, v[2:3]
	global_load_dwordx4 v[88:91], v[4:5], off
	v_cndmask_b32_e32 v5, v147, v151, vcc
	v_cndmask_b32_e32 v4, v146, v150, vcc
	v_lshl_add_u64 v[2:3], v[4:5], 0, v[2:3]
	global_load_dwordx4 v[92:95], v[2:3], off
	v_add_u32_e32 v2, 16, v1
	v_min_i32_e32 v2, s53, v2
	v_mul_u32_u24_e32 v2, v2, v177
	v_add_u32_e32 v2, v2, v178
	v_add_u32_e32 v3, -8, v2
	v_cmp_lt_i32_e32 vcc, v2, v180
	s_add_i32 s49, s53, -8
	s_add_i32 s56, s53, -12
	v_cndmask_b32_e32 v2, v3, v2, vcc
	v_mul_u32_u24_e32 v2, v2, v141
	v_mov_b32_e32 v3, 0
	v_or_b32_e32 v2, v2, v130
	v_cndmask_b32_e32 v5, v145, v149, vcc
	v_cndmask_b32_e32 v4, v144, v148, vcc
	v_lshlrev_b32_e32 v2, 2, v2
	v_lshl_add_u64 v[4:5], v[4:5], 0, v[2:3]
	global_load_dwordx4 v[80:83], v[4:5], off
	v_cndmask_b32_e32 v5, v147, v151, vcc
	v_cndmask_b32_e32 v4, v146, v150, vcc
	v_lshl_add_u64 v[2:3], v[4:5], 0, v[2:3]
	global_load_dwordx4 v[84:87], v[2:3], off
	v_add_u32_e32 v2, 20, v1
	v_min_i32_e32 v2, s53, v2
	v_mul_u32_u24_e32 v2, v2, v177
	v_add_u32_e32 v2, v2, v178
	v_add_u32_e32 v3, -8, v2
	v_cmp_lt_i32_e32 vcc, v2, v180
	s_add_i32 s42, s53, -16
	s_sub_i32 s54, s53, 20
	v_cndmask_b32_e32 v2, v3, v2, vcc
	v_mul_u32_u24_e32 v2, v2, v141
	v_mov_b32_e32 v3, 0
	v_or_b32_e32 v2, v2, v130
	v_cndmask_b32_e32 v5, v145, v149, vcc
	v_cndmask_b32_e32 v4, v144, v148, vcc
	v_lshlrev_b32_e32 v2, 2, v2
	v_lshl_add_u64 v[4:5], v[4:5], 0, v[2:3]
	global_load_dwordx4 v[64:67], v[4:5], off
	v_cndmask_b32_e32 v5, v147, v151, vcc
	v_cndmask_b32_e32 v4, v146, v150, vcc
	v_lshl_add_u64 v[2:3], v[4:5], 0, v[2:3]
	global_load_dwordx4 v[68:71], v[2:3], off
	v_add_u32_e32 v2, 24, v1
	v_min_i32_e32 v2, s53, v2
	v_mul_u32_u24_e32 v2, v2, v177
	v_add_u32_e32 v2, v2, v178
	v_add_u32_e32 v3, -8, v2
	v_cmp_lt_i32_e32 vcc, v2, v180
	s_sub_i32 s50, s53, 24
	s_sub_i32 s34, s53, 28
	v_cndmask_b32_e32 v2, v3, v2, vcc
	v_mul_u32_u24_e32 v2, v2, v141
	v_mov_b32_e32 v3, 0
	v_or_b32_e32 v2, v2, v130
	v_cndmask_b32_e32 v5, v145, v149, vcc
	v_cndmask_b32_e32 v4, v144, v148, vcc
	v_lshlrev_b32_e32 v2, 2, v2
	v_lshl_add_u64 v[4:5], v[4:5], 0, v[2:3]
	global_load_dwordx4 v[72:75], v[4:5], off
	v_cndmask_b32_e32 v5, v147, v151, vcc
	v_cndmask_b32_e32 v4, v146, v150, vcc
	v_lshl_add_u64 v[2:3], v[4:5], 0, v[2:3]
	global_load_dwordx4 v[76:79], v[2:3], off
	v_add_u32_e32 v2, 28, v1
	v_min_i32_e32 v2, s53, v2
	v_mul_u32_u24_e32 v2, v2, v177
	v_add_u32_e32 v2, v2, v178
	v_add_u32_e32 v3, -8, v2
	v_cmp_lt_i32_e32 vcc, v2, v180
	s_add_i32 s18, s51, 32
	v_add_u32_e32 v182, v159, v179
	v_cndmask_b32_e32 v2, v3, v2, vcc
	v_mul_u32_u24_e32 v2, v2, v141
	v_mov_b32_e32 v3, 0
	v_or_b32_e32 v2, v2, v130
	v_cndmask_b32_e32 v5, v145, v149, vcc
	v_cndmask_b32_e32 v4, v144, v148, vcc
	v_lshlrev_b32_e32 v2, 2, v2
	v_lshl_add_u64 v[4:5], v[4:5], 0, v[2:3]
	global_load_dwordx4 v[32:35], v[4:5], off
	v_cndmask_b32_e32 v5, v147, v151, vcc
	v_cndmask_b32_e32 v4, v146, v150, vcc
	v_lshl_add_u64 v[2:3], v[4:5], 0, v[2:3]
	global_load_dwordx4 v[36:39], v[2:3], off
	v_and_b32_e32 v3, 64, v128
	v_xor_b32_e32 v2, 32, v128
	v_add_u32_e32 v3, 64, v3
	v_cmp_lt_i32_e32 vcc, v2, v3
	v_cmp_ne_u32_e64 s[8:9], 1, v0
	v_add_u32_e32 v0, v158, v139
	v_cndmask_b32_e32 v2, v128, v2, vcc
	v_lshlrev_b32_e32 v143, 2, v2
	v_add_u32_e32 v2, v160, v179
	v_sub_u32_e32 v181, v0, v179
	v_add_u32_e32 v0, -8, v178
	v_mul_lo_u32 v183, v177, v2
	v_add_u32_e32 v2, v0, v183
	v_mul_lo_u32 v184, v141, v2
	v_add_u32_e32 v2, v161, v179
	v_mul_lo_u32 v187, v177, v2
	v_add_u32_e32 v2, v0, v187
	v_mul_lo_u32 v188, v141, v2
	v_add_u32_e32 v2, v162, v179
	v_mul_lo_u32 v189, v177, v2
	v_add_u32_e32 v2, v0, v189
	v_mul_lo_u32 v190, v141, v2
	v_add_u32_e32 v2, v163, v179
	v_mul_lo_u32 v191, v177, v2
	v_add_u32_e32 v2, v0, v191
	v_mul_lo_u32 v192, v141, v2
	v_add_u32_e32 v2, v167, v179
	v_mul_lo_u32 v193, v177, v2
	v_add_u32_e32 v2, v0, v193
	v_mul_lo_u32 v194, v141, v2
	v_add_u32_e32 v2, v168, v179
	v_mul_lo_u32 v195, v177, v2
	v_add_u32_e32 v2, v0, v195
	v_mul_lo_u32 v196, v141, v2
	v_add_u32_e32 v2, v169, v179
	v_mul_lo_u32 v197, v177, v2
	v_add_u32_e32 v2, v0, v197
	v_add_u32_e32 v0, v0, v199
	v_mul_lo_u32 v186, v185, v141
	v_mul_lo_u32 v198, v141, v2
	v_mul_lo_u32 v200, v141, v0
	v_mov_b32_e32 v208, 0xf149f2ca
	v_mov_b32_e32 v201, v178
	v_mov_b32_e32 v16, 0
	v_mov_b32_e32 v17, v202
	v_mov_b32_e32 v18, v202
	v_mov_b32_e32 v19, v202
	v_mov_b32_e32 v20, v202
	v_mov_b32_e32 v21, v202
	v_mov_b32_e32 v22, v202
	v_mov_b32_e32 v23, v202
	v_mov_b32_e32 v24, v202
	v_mov_b32_e32 v25, v202
	v_mov_b32_e32 v26, v202
	v_mov_b32_e32 v27, v202
	v_mov_b32_e32 v28, v202
	v_mov_b32_e32 v29, v202
	v_mov_b32_e32 v30, v202
	v_mov_b32_e32 v31, v202
	v_mov_b32_e32 v0, 0
	v_mov_b32_e32 v1, v202
	v_mov_b32_e32 v2, v202
	v_mov_b32_e32 v3, v202
	v_mov_b32_e32 v4, v202
	v_mov_b32_e32 v5, v202
	v_mov_b32_e32 v6, v202
	v_mov_b32_e32 v7, v202
	v_mov_b32_e32 v8, v202
	v_mov_b32_e32 v9, v202
	v_mov_b32_e32 v10, v202
	v_mov_b32_e32 v11, v202
	v_mov_b32_e32 v12, v202
	v_mov_b32_e32 v13, v202
	v_mov_b32_e32 v14, v202
	v_mov_b32_e32 v15, v202

.LBB0_1326:
	v_subrev_u32_e32 v32, 28, v182
	v_min_i32_e32 v32, s53, v32
	v_mul_u32_u24_e32 v32, v32, v177
	v_add_u32_e32 v32, v32, v178
	v_add_u32_e32 v33, -8, v32
	v_cmp_lt_i32_e32 vcc, v32, v180
	v_add_u32_e32 v211, v127, v129
	ds_read_b128 v[216:219], v211 offset:64
	v_cndmask_b32_e32 v32, v33, v32, vcc
	v_mul_u32_u24_e32 v32, v32, v141
	v_mov_b32_e32 v33, 0
	v_or_b32_e32 v32, v32, v130
	v_cndmask_b32_e32 v35, v145, v149, vcc
	v_cndmask_b32_e32 v34, v144, v148, vcc
	v_lshlrev_b32_e32 v32, 2, v32
	v_lshl_add_u64 v[34:35], v[34:35], 0, v[32:33]
	global_load_dwordx4 v[112:115], v[34:35], off
	v_cndmask_b32_e32 v35, v147, v151, vcc
	v_cndmask_b32_e32 v34, v146, v150, vcc
	v_lshl_add_u64 v[32:33], v[34:35], 0, v[32:33]
	global_load_dwordx4 v[116:119], v[32:33], off
	v_subrev_u32_e32 v32, 24, v182
	v_min_i32_e32 v32, s53, v32
	v_mul_u32_u24_e32 v32, v32, v177
	v_add_u32_e32 v32, v32, v178
	v_add_u32_e32 v33, -8, v32
	v_cmp_lt_i32_e32 vcc, v32, v180
	v_min_i32_e32 v120, s53, v182
	v_mul_u32_u24_e32 v120, v120, v177
	v_cndmask_b32_e32 v32, v33, v32, vcc
	v_mul_u32_u24_e32 v32, v32, v141
	v_mov_b32_e32 v33, 0
	v_or_b32_e32 v32, v32, v130
	v_cndmask_b32_e32 v35, v145, v149, vcc
	v_cndmask_b32_e32 v34, v144, v148, vcc
	v_lshlrev_b32_e32 v32, 2, v32
	v_lshl_add_u64 v[34:35], v[34:35], 0, v[32:33]
	global_load_dwordx4 v[104:107], v[34:35], off
	v_cndmask_b32_e32 v35, v147, v151, vcc
	v_cndmask_b32_e32 v34, v146, v150, vcc
	v_lshl_add_u64 v[32:33], v[34:35], 0, v[32:33]
	global_load_dwordx4 v[108:111], v[32:33], off
	v_subrev_u32_e32 v32, 20, v182
	v_min_i32_e32 v32, s53, v32
	v_mul_u32_u24_e32 v32, v32, v177
	v_add_u32_e32 v32, v32, v178
	v_add_u32_e32 v33, -8, v32
	v_cmp_lt_i32_e32 vcc, v32, v180
	v_add_u32_e32 v120, v120, v178
	v_add_u32_e32 v209, -8, v120
	v_cndmask_b32_e32 v32, v33, v32, vcc
	v_mul_u32_u24_e32 v32, v32, v141
	v_mov_b32_e32 v33, 0
	v_or_b32_e32 v32, v32, v130
	v_cndmask_b32_e32 v35, v145, v149, vcc
	v_cndmask_b32_e32 v34, v144, v148, vcc
	v_lshlrev_b32_e32 v32, 2, v32
	v_lshl_add_u64 v[34:35], v[34:35], 0, v[32:33]
	global_load_dwordx4 v[96:99], v[34:35], off
	v_cndmask_b32_e32 v35, v147, v151, vcc
	v_cndmask_b32_e32 v34, v146, v150, vcc
	v_lshl_add_u64 v[32:33], v[34:35], 0, v[32:33]
	global_load_dwordx4 v[100:103], v[32:33], off
	v_add_u32_e32 v32, -16, v182
	v_min_i32_e32 v32, s53, v32
	v_mul_u32_u24_e32 v32, v32, v177
	v_add_u32_e32 v32, v32, v178
	v_add_u32_e32 v33, -8, v32
	v_cmp_lt_i32_e32 vcc, v32, v180
	v_add_u32_e32 v184, v184, v186
	v_add_u32_e32 v201, v201, v185
	v_cndmask_b32_e32 v32, v33, v32, vcc
	v_mul_u32_u24_e32 v32, v32, v141
	v_mov_b32_e32 v33, 0
	v_or_b32_e32 v32, v32, v130
	v_cndmask_b32_e32 v35, v145, v149, vcc
	v_cndmask_b32_e32 v34, v144, v148, vcc
	v_lshlrev_b32_e32 v32, 2, v32
	v_lshl_add_u64 v[34:35], v[34:35], 0, v[32:33]
	global_load_dwordx4 v[88:91], v[34:35], off
	v_cndmask_b32_e32 v35, v147, v151, vcc
	v_cndmask_b32_e32 v34, v146, v150, vcc
	v_lshl_add_u64 v[32:33], v[34:35], 0, v[32:33]
	global_load_dwordx4 v[92:95], v[32:33], off
	v_add_u32_e32 v32, -12, v182
	v_min_i32_e32 v32, s53, v32
	v_mul_u32_u24_e32 v32, v32, v177
	v_add_u32_e32 v32, v32, v178
	v_add_u32_e32 v33, -8, v32
	v_cmp_lt_i32_e32 vcc, v32, v180
	ds_read_b128 v[212:215], v211 offset:32
	v_add_u32_e32 v188, v188, v186
	v_cndmask_b32_e32 v32, v33, v32, vcc
	v_mul_u32_u24_e32 v32, v32, v141
	v_mov_b32_e32 v33, 0
	v_or_b32_e32 v32, v32, v130
	v_cndmask_b32_e32 v35, v145, v149, vcc
	v_cndmask_b32_e32 v34, v144, v148, vcc
	v_lshlrev_b32_e32 v32, 2, v32
	v_lshl_add_u64 v[34:35], v[34:35], 0, v[32:33]
	global_load_dwordx4 v[80:83], v[34:35], off
	v_cndmask_b32_e32 v35, v147, v151, vcc
	v_cndmask_b32_e32 v34, v146, v150, vcc
	v_lshl_add_u64 v[32:33], v[34:35], 0, v[32:33]
	global_load_dwordx4 v[84:87], v[32:33], off
	v_add_u32_e32 v32, -8, v182
	v_min_i32_e32 v32, s53, v32
	v_mul_u32_u24_e32 v32, v32, v177
	v_add_u32_e32 v32, v32, v178
	v_add_u32_e32 v33, -8, v32
	v_cmp_lt_i32_e32 vcc, v32, v180
	v_add_u32_e32 v190, v190, v186
	v_add_u32_e32 v192, v192, v186
	v_cndmask_b32_e32 v32, v33, v32, vcc
	v_mul_u32_u24_e32 v32, v32, v141
	v_mov_b32_e32 v33, 0
	v_or_b32_e32 v32, v32, v130
	v_cndmask_b32_e32 v35, v145, v149, vcc
	v_cndmask_b32_e32 v34, v144, v148, vcc
	v_lshlrev_b32_e32 v32, 2, v32
	v_lshl_add_u64 v[34:35], v[34:35], 0, v[32:33]
	global_load_dwordx4 v[64:67], v[34:35], off
	v_cndmask_b32_e32 v35, v147, v151, vcc
	v_cndmask_b32_e32 v34, v146, v150, vcc
	v_lshl_add_u64 v[32:33], v[34:35], 0, v[32:33]
	global_load_dwordx4 v[68:71], v[32:33], off
	v_add_u32_e32 v32, -4, v182
	v_min_i32_e32 v32, s53, v32
	v_mul_u32_u24_e32 v32, v32, v177
	v_add_u32_e32 v32, v32, v178
	v_add_u32_e32 v33, -8, v32
	v_cmp_lt_i32_e32 vcc, v32, v180
	v_add_u32_e32 v182, 32, v182
	v_add_u32_e32 v194, v194, v186
	v_cndmask_b32_e32 v32, v33, v32, vcc
	v_mul_u32_u24_e32 v32, v32, v141
	v_or_b32_e32 v36, v32, v130
	v_mov_b32_e32 v37, 0
	ds_read_b128 v[32:35], v211
	v_cndmask_b32_e32 v39, v145, v149, vcc
	v_cndmask_b32_e32 v38, v144, v148, vcc
	v_lshlrev_b64 v[76:77], 2, v[36:37]
	v_lshl_add_u64 v[36:37], v[38:39], 0, v[76:77]
	global_load_dwordx4 v[72:75], v[36:37], off
	s_waitcnt lgkmcnt(0)
	v_mfma_f32_32x32x16_bf16 v[32:47], v[32:35], v[56:59], 0
	v_cndmask_b32_e32 v79, v147, v151, vcc
	v_cndmask_b32_e32 v78, v146, v150, vcc
	v_cmp_lt_i32_e32 vcc, v120, v180
	v_lshl_add_u64 v[76:77], v[78:79], 0, v[76:77]
	global_load_dwordx4 v[76:79], v[76:77], off
	v_cndmask_b32_e32 v120, v209, v120, vcc
	v_mul_u32_u24_e32 v220, v120, v141
	v_mfma_f32_32x32x16_bf16 v[32:47], v[212:215], v[60:63], v[32:47]
	ds_read_b128 v[212:215], v211 offset:96
	v_add_u32_e32 v196, v196, v186
	v_add_u32_e32 v198, v198, v186
	v_add_u32_e32 v200, v200, v186
	v_mfma_f32_32x32x16_bf16 v[32:47], v[216:219], v[52:55], v[32:47]
	v_add_u32_e32 v120, s33, v181
	v_cmp_le_u32_e64 s[16:17], v120, v135
	v_or_b32_e32 v218, v220, v130
	v_mov_b32_e32 v219, 0
	v_cndmask_b32_e32 v217, v145, v149, vcc
	s_waitcnt lgkmcnt(0)
	v_mfma_f32_32x32x16_bf16 v[32:47], v[212:215], v[48:51], v[32:47]
	v_cndmask_b32_e32 v216, v144, v148, vcc
	v_lshlrev_b64 v[218:219], 2, v[218:219]
	s_sub_i32 s33, s33, 32
	s_nop 8
	v_cndmask_b32_e64 v210, v173, v32, s[16:17]
	v_add_u32_e32 v32, -1, v120
	v_cmp_le_u32_e64 s[16:17], v32, v135
	s_nop 1
	v_cndmask_b32_e64 v212, v173, v33, s[16:17]
	v_add_u32_e32 v33, -2, v120
	v_cmp_le_u32_e64 s[16:17], v33, v135
	v_add_u32_e32 v33, -3, v120
	v_max3_f32 v32, v210, s90, v212
	v_cndmask_b32_e64 v213, v173, v34, s[16:17]
	v_cmp_le_u32_e64 s[16:17], v33, v135
	v_add_u32_e32 v33, -8, v120
	s_nop 0
	v_cndmask_b32_e64 v214, v173, v35, s[16:17]
	v_cmp_le_u32_e64 s[16:17], v33, v135
	v_add_u32_e32 v33, -9, v120
	v_max3_f32 v32, v32, v213, v214
	v_cndmask_b32_e64 v215, v173, v36, s[16:17]
	v_cmp_le_u32_e64 s[16:17], v33, v135
	v_add_u32_e32 v33, -10, v120
	v_cndmask_b32_e32 v36, v146, v150, vcc
	v_cndmask_b32_e64 v220, v173, v37, s[16:17]
	v_cmp_le_u32_e64 s[16:17], v33, v135
	v_add_u32_e32 v33, -11, v120
	v_max3_f32 v32, v32, v215, v220
	v_cndmask_b32_e64 v221, v173, v38, s[16:17]
	v_cmp_le_u32_e64 s[16:17], v33, v135
	v_add_u32_e32 v33, -16, v120
	v_cndmask_b32_e32 v37, v147, v151, vcc
	v_cndmask_b32_e64 v222, v173, v39, s[16:17]
	v_cmp_le_u32_e64 s[16:17], v33, v135
	v_subrev_u32_e32 v33, 17, v120
	v_max3_f32 v32, v32, v221, v222
	v_cndmask_b32_e64 v40, v173, v40, s[16:17]
	v_cmp_le_u32_e64 s[16:17], v33, v135
	v_subrev_u32_e32 v33, 18, v120
	v_lshl_add_u64 v[36:37], v[36:37], 0, v[218:219]
	v_cndmask_b32_e64 v41, v173, v41, s[16:17]
	v_cmp_le_u32_e64 s[16:17], v33, v135
	v_subrev_u32_e32 v33, 19, v120
	v_max3_f32 v32, v32, v40, v41
	v_cndmask_b32_e64 v42, v173, v42, s[16:17]
	v_cmp_le_u32_e64 s[16:17], v33, v135
	v_subrev_u32_e32 v33, 24, v120
	s_nop 0
	v_cndmask_b32_e64 v43, v173, v43, s[16:17]
	v_cmp_le_u32_e64 s[16:17], v33, v135
	v_subrev_u32_e32 v33, 25, v120
	v_max3_f32 v32, v32, v42, v43
	v_cndmask_b32_e64 v44, v173, v44, s[16:17]
	v_cmp_le_u32_e64 s[16:17], v33, v135
	v_subrev_u32_e32 v33, 26, v120
	s_nop 0
	v_cndmask_b32_e64 v45, v173, v45, s[16:17]
	v_cmp_le_u32_e64 s[16:17], v33, v135
	v_subrev_u32_e32 v33, 27, v120
	v_max3_f32 v32, v32, v44, v45
	v_cndmask_b32_e64 v46, v173, v46, s[16:17]
	v_cmp_le_u32_e64 s[16:17], v33, v135
	s_nop 1
	v_cndmask_b32_e64 v47, v173, v47, s[16:17]
	v_max3_f32 v38, v32, v46, v47
	ds_bpermute_b32 v39, v143, v38
	v_lshl_add_u64 v[32:33], v[216:217], 0, v[218:219]
	global_load_dwordx4 v[32:35], v[32:33], off
	s_add_i32 s16, s18, s33
	s_cmp_lg_u32 s16, 0
	s_waitcnt lgkmcnt(0)
	v_max3_f32 v209, v208, v38, v39
	v_sub_f32_e32 v38, v210, v209
	v_exp_f32_e32 v210, v38
	global_load_dwordx4 v[36:39], v[36:37], off
	v_sub_f32_e32 v212, v212, v209
	v_exp_f32_e32 v212, v212
	v_sub_f32_e32 v213, v213, v209
	v_exp_f32_e32 v213, v213
	v_sub_f32_e32 v214, v214, v209
	v_exp_f32_e32 v214, v214
	v_sub_f32_e32 v215, v215, v209
	v_sub_f32_e32 v120, v208, v209
	v_add_f32_e32 v208, 0, v210
	v_exp_f32_e32 v215, v215
	v_sub_f32_e32 v216, v220, v209
	v_add_f32_e32 v208, v212, v208
	v_exp_f32_e32 v216, v216
	v_sub_f32_e32 v217, v221, v209
	v_add_f32_e32 v208, v213, v208
	v_exp_f32_e32 v217, v217
	v_sub_f32_e32 v218, v222, v209
	v_add_f32_e32 v208, v214, v208
	v_exp_f32_e32 v218, v218
	v_sub_f32_e32 v40, v40, v209
	v_add_f32_e32 v208, v215, v208
	v_exp_f32_e32 v220, v40
	v_sub_f32_e32 v41, v41, v209
	v_add_f32_e32 v40, v216, v208
	v_exp_f32_e32 v208, v41
	v_sub_f32_e32 v41, v42, v209
	v_add_f32_e32 v40, v217, v40
	v_exp_f32_e32 v221, v41
	v_sub_f32_e32 v41, v43, v209
	v_add_f32_e32 v40, v218, v40
	v_exp_f32_e32 v222, v41
	v_sub_f32_e32 v41, v44, v209
	v_add_f32_e32 v40, v220, v40
	v_exp_f32_e32 v223, v41
	v_sub_f32_e32 v41, v45, v209
	v_add_f32_e32 v40, v208, v40
	v_exp_f32_e32 v224, v41
	v_sub_f32_e32 v41, v46, v209
	v_add_f32_e32 v40, v221, v40
	v_exp_f32_e32 v225, v41
	v_sub_f32_e32 v41, v47, v209
	v_add_f32_e32 v40, v222, v40
	v_exp_f32_e32 v226, v41
	v_add_f32_e32 v40, v223, v40
	v_add_f32_e32 v40, v224, v40
	v_add_f32_e32 v40, v225, v40
	v_exp_f32_e32 v120, v120
	v_add_f32_e32 v227, v226, v40
	ds_read_b64_tr_b16 v[40:41], v175 offset:4608
	ds_read_b64_tr_b16 v[42:43], v175 offset:5760
	v_cvt_pk_bf16_f32 v44, v210, v212
	v_cvt_pk_bf16_f32 v45, v213, v214
	v_cvt_pk_bf16_f32 v46, v215, v216
	v_cvt_pk_bf16_f32 v47, v217, v218
	ds_read_b64_tr_b16 v[212:213], v175 offset:6912
	ds_read_b64_tr_b16 v[214:215], v175 offset:8064
	ds_read_b64_tr_b16 v[218:219], v175 offset:5824
	ds_read_b64_tr_b16 v[216:217], v175 offset:4672
	v_pk_mul_f32 v[14:15], v[14:15], v[120:121] op_sel_hi:[1,0]
	v_pk_mul_f32 v[12:13], v[12:13], v[120:121] op_sel_hi:[1,0]
	v_pk_mul_f32 v[10:11], v[10:11], v[120:121] op_sel_hi:[1,0]
	v_pk_mul_f32 v[8:9], v[8:9], v[120:121] op_sel_hi:[1,0]
	v_pk_mul_f32 v[6:7], v[6:7], v[120:121] op_sel_hi:[1,0]
	v_pk_mul_f32 v[4:5], v[4:5], v[120:121] op_sel_hi:[1,0]
	v_pk_mul_f32 v[2:3], v[2:3], v[120:121] op_sel_hi:[1,0]
	v_pk_mul_f32 v[0:1], v[0:1], v[120:121] op_sel_hi:[1,0]
	v_pk_mul_f32 v[30:31], v[30:31], v[120:121] op_sel_hi:[1,0]
	v_pk_mul_f32 v[28:29], v[28:29], v[120:121] op_sel_hi:[1,0]
	v_pk_mul_f32 v[26:27], v[26:27], v[120:121] op_sel_hi:[1,0]
	v_pk_mul_f32 v[24:25], v[24:25], v[120:121] op_sel_hi:[1,0]
	v_pk_mul_f32 v[22:23], v[22:23], v[120:121] op_sel_hi:[1,0]
	v_pk_mul_f32 v[20:21], v[20:21], v[120:121] op_sel_hi:[1,0]
	v_pk_mul_f32 v[18:19], v[18:19], v[120:121] op_sel_hi:[1,0]
	v_pk_mul_f32 v[16:17], v[16:17], v[120:121] op_sel_hi:[1,0]
	s_waitcnt lgkmcnt(4)
	v_mfma_f32_32x32x16_bf16 v[0:15], v[40:43], v[44:47], v[0:15]
	v_cvt_pk_bf16_f32 v40, v220, v208
	v_cvt_pk_bf16_f32 v41, v221, v222
	v_cvt_pk_bf16_f32 v42, v223, v224
	ds_read_b64_tr_b16 v[222:223], v175 offset:8128
	ds_read_b64_tr_b16 v[220:221], v175 offset:6976
	v_cvt_pk_bf16_f32 v43, v225, v226
	s_waitcnt lgkmcnt(2)
	v_mfma_f32_32x32x16_bf16 v[16:31], v[216:219], v[44:47], v[16:31]
	ds_bpermute_b32 v44, v143, v227
	s_waitcnt lgkmcnt(0)
	v_add_f32_e32 v210, v227, v44
	v_fmac_f32_e32 v210, v202, v120
	v_mfma_f32_32x32x16_bf16 v[0:15], v[212:215], v[40:43], v[0:15]
	v_mfma_f32_32x32x16_bf16 v[16:31], v[220:223], v[40:43], v[16:31]
	s_cbranch_scc0 .LBB0_1328
	v_mov_b32_e32 v208, v209
	v_mov_b32_e32 v202, v210
	s_branch .LBB0_1284
